# down gemm loop: LDS fragment-read base arithmetic hoisted into immediates (no VALU left in down load phases), on top of v34
# speedup vs baseline: 1.0064x; 1.0064x over previous
; #define PG8_STAGE(bufoff, gbase, voff) do { _Pragma("unroll") for (int _i = 0; _i < 2; ++_i) \
;         __builtin_amdgcn_global_load_lds((const unsigned*)((const char*)(gbase) + (voff)[_i]), (LAS unsigned*)(lds + (bufoff) + ldsw + _i * 8192), 16, 0, 0); } while (0)
; #define PG8_WAIT_V(n) asm volatile("s_waitcnt vmcnt(" #n ")" ::: "memory")
; #define PG8_BAR __builtin_amdgcn_s_barrier()
; template <class Epi, class Addr>
; __device__ __forceinline__ void gemm_phase(LAS unsigned char* lds, const Gemm g, const StaticOrder& S, const Addr& AD, const Epi& E) {
;     ...
;     Acc acc;
; #pragma unroll
;     for (int a = 0; a < 2; ++a)
; #pragma unroll
;         for (int b = 0; b < 2; ++b)
; #pragma unroll
;             for (int m = 0; m < 4; ++m)
; #pragma unroll
;                 for (int n = 0; n < 2; ++n) acc[a][b][m][n] = (f32x4){0.f, 0.f, 0.f, 0.f};
;     bf16x8 At[4][2], B0[2][2], B1[2][2];
;     const char* cA; const char* cB; AD.get(g, cur, cA, cB);
;     PG8_STAGE(PG8_SB(0, 0), cB, voffB); PG8_STAGE(PG8_SB(0, 1), cB + hstepB, voffB); PG8_STAGE(PG8_SA(0, 0), cA, voffA); PG8_STAGE(PG8_SA(0, 1), cA + hstepA, voffA);
;     if (wr == 1) PG8_BAR;
;     PG8_WAIT_V(2); PG8_BAR;
;     PG8_STAGE(PG8_SB(1, 0), cB + kstep, voffB); PG8_STAGE(PG8_SA(1, 0), cA + kstep, voffA); PG8_STAGE(PG8_SB(1, 1), cB + hstepB + kstep, voffB);
;     PG8_WAIT_V(6); PG8_BAR;
;     for (;;) {
;         const bool has_next = S.next(ui + 1, nxt);
;         const char* nA = cA; const char* nB = cB; if (has_next) AD.get(g, nxt, nA, nB);
;         for (int t = 0; t < nt; t += 2) {
.LBB0_1330:
	v_mov_b32_e32 v189, 0
	s_andn2_b64 vcc, exec, s[58:59]
	v_mov_b32_e32 v188, 0
	v_mov_b32_e32 v227, 0
	v_mov_b32_e32 v226, 0
	v_mov_b32_e32 v197, 0
	v_mov_b32_e32 v196, 0
	v_mov_b32_e32 v195, 0
	v_mov_b32_e32 v194, 0
	v_mov_b32_e32 v185, 0
	v_mov_b32_e32 v184, 0
	v_mov_b32_e32 v187, 0
	v_mov_b32_e32 v186, 0
	v_mov_b32_e32 v179, 0
	v_mov_b32_e32 v178, 0
	v_mov_b32_e32 v177, 0
	v_mov_b32_e32 v176, 0
	v_mov_b32_e32 v165, 0
	v_mov_b32_e32 v164, 0
	v_mov_b32_e32 v167, 0
	v_mov_b32_e32 v166, 0
	v_mov_b32_e32 v159, 0
	v_mov_b32_e32 v158, 0
	v_mov_b32_e32 v157, 0
	v_mov_b32_e32 v156, 0
	v_mov_b32_e32 v149, 0
	v_mov_b32_e32 v148, 0
	v_mov_b32_e32 v151, 0
	v_mov_b32_e32 v150, 0
	v_mov_b32_e32 v143, 0
	v_mov_b32_e32 v142, 0
	v_mov_b32_e32 v141, 0
	v_mov_b32_e32 v140, 0
	v_mov_b32_e32 v223, 0
	v_mov_b32_e32 v222, 0
	v_mov_b32_e32 v199, 0
	v_mov_b32_e32 v198, 0
	v_mov_b32_e32 v193, 0
	v_mov_b32_e32 v192, 0
	v_mov_b32_e32 v191, 0
	v_mov_b32_e32 v190, 0
	v_mov_b32_e32 v183, 0
	v_mov_b32_e32 v182, 0
	v_mov_b32_e32 v181, 0
	v_mov_b32_e32 v180, 0
	v_mov_b32_e32 v171, 0
	v_mov_b32_e32 v170, 0
	v_mov_b32_e32 v169, 0
	v_mov_b32_e32 v168, 0
	v_mov_b32_e32 v163, 0
	v_mov_b32_e32 v162, 0
	v_mov_b32_e32 v161, 0
	v_mov_b32_e32 v160, 0
	v_mov_b32_e32 v155, 0
	v_mov_b32_e32 v154, 0
	v_mov_b32_e32 v153, 0
	v_mov_b32_e32 v152, 0
	v_mov_b32_e32 v147, 0
	v_mov_b32_e32 v146, 0
	v_mov_b32_e32 v145, 0
	v_mov_b32_e32 v144, 0
	v_mov_b32_e32 v139, 0
	v_mov_b32_e32 v138, 0
	v_mov_b32_e32 v137, 0
	v_mov_b32_e32 v136, 0
	v_mov_b32_e32 v127, 0
	v_mov_b32_e32 v126, 0
	v_mov_b32_e32 v135, 0
	v_mov_b32_e32 v134, 0
	v_mov_b32_e32 v119, 0
	v_mov_b32_e32 v118, 0
	v_mov_b32_e32 v117, 0
	v_mov_b32_e32 v116, 0
	v_mov_b32_e32 v111, 0
	v_mov_b32_e32 v110, 0
	v_mov_b32_e32 v109, 0
	v_mov_b32_e32 v108, 0
	v_mov_b32_e32 v103, 0
	v_mov_b32_e32 v102, 0
	v_mov_b32_e32 v101, 0
	v_mov_b32_e32 v100, 0
	v_mov_b32_e32 v95, 0
	v_mov_b32_e32 v94, 0
	v_mov_b32_e32 v93, 0
	v_mov_b32_e32 v92, 0
	v_mov_b32_e32 v87, 0
	v_mov_b32_e32 v86, 0
	v_mov_b32_e32 v85, 0
	v_mov_b32_e32 v84, 0
	v_mov_b32_e32 v79, 0
	v_mov_b32_e32 v78, 0
	v_mov_b32_e32 v77, 0
	v_mov_b32_e32 v76, 0
	v_mov_b32_e32 v71, 0
	v_mov_b32_e32 v70, 0
	v_mov_b32_e32 v69, 0
	v_mov_b32_e32 v68, 0
	v_mov_b32_e32 v123, 0
	v_mov_b32_e32 v122, 0
	v_mov_b32_e32 v121, 0
	v_mov_b32_e32 v120, 0
	v_mov_b32_e32 v115, 0
	v_mov_b32_e32 v114, 0
	v_mov_b32_e32 v113, 0
	v_mov_b32_e32 v112, 0
	v_mov_b32_e32 v107, 0
	v_mov_b32_e32 v106, 0
	v_mov_b32_e32 v105, 0
	v_mov_b32_e32 v104, 0
	v_mov_b32_e32 v99, 0
	v_mov_b32_e32 v98, 0
	v_mov_b32_e32 v97, 0
	v_mov_b32_e32 v96, 0
	v_mov_b32_e32 v91, 0
	v_mov_b32_e32 v90, 0
	v_mov_b32_e32 v89, 0
	v_mov_b32_e32 v88, 0
	v_mov_b32_e32 v83, 0
	v_mov_b32_e32 v82, 0
	v_mov_b32_e32 v81, 0
	v_mov_b32_e32 v80, 0
	v_mov_b32_e32 v75, 0
	v_mov_b32_e32 v74, 0
	v_mov_b32_e32 v73, 0
	v_mov_b32_e32 v72, 0
	v_mov_b32_e32 v67, 0
	v_mov_b32_e32 v66, 0
	v_mov_b32_e32 v65, 0
	v_mov_b32_e32 v64, 0
	s_cbranch_vccnz .LBB0_1334
	s_add_u32 s79, s66, 0x100
	v_mov_b32_e32 v0, 0
	s_addc_u32 s80, s67, 0
	s_mov_b32 s66, 0
	s_waitcnt lgkmcnt(0)
	v_mov_b32_e32 v1, v0
	v_mov_b32_e32 v2, v0
	v_mov_b32_e32 v3, v0
	v_mov_b32_e32 v4, v0
	v_mov_b32_e32 v5, v0
	v_mov_b32_e32 v6, v0
	v_mov_b32_e32 v7, v0
	v_mov_b32_e32 v8, v0
	v_mov_b32_e32 v9, v0
	v_mov_b32_e32 v10, v0
	v_mov_b32_e32 v11, v0
	v_mov_b32_e32 v12, v0
	v_mov_b32_e32 v13, v0
	v_mov_b32_e32 v14, v0
	v_mov_b32_e32 v15, v0
	v_mov_b32_e32 v20, v0
	v_mov_b32_e32 v21, v0
	v_mov_b32_e32 v22, v0
	v_mov_b32_e32 v23, v0
	v_mov_b32_e32 v28, v0
	v_mov_b32_e32 v29, v0
	v_mov_b32_e32 v30, v0
	v_mov_b32_e32 v31, v0
	v_mov_b32_e32 v36, v0
	v_mov_b32_e32 v37, v0
	v_mov_b32_e32 v38, v0
	v_mov_b32_e32 v39, v0
	v_mov_b32_e32 v44, v0
	v_mov_b32_e32 v45, v0
	v_mov_b32_e32 v46, v0
	v_mov_b32_e32 v47, v0
	v_mov_b32_e32 v16, v0
	v_mov_b32_e32 v17, v0
	v_mov_b32_e32 v18, v0
	v_mov_b32_e32 v19, v0
	v_mov_b32_e32 v24, v0
	v_mov_b32_e32 v25, v0
	v_mov_b32_e32 v26, v0
	v_mov_b32_e32 v27, v0
	v_mov_b32_e32 v32, v0
	v_mov_b32_e32 v33, v0
	v_mov_b32_e32 v34, v0
	v_mov_b32_e32 v35, v0
	v_mov_b32_e32 v40, v0
	v_mov_b32_e32 v41, v0
	v_mov_b32_e32 v42, v0
	v_mov_b32_e32 v43, v0
	v_mov_b32_e32 v48, v0
	v_mov_b32_e32 v49, v0
	v_mov_b32_e32 v50, v0
	v_mov_b32_e32 v51, v0
	v_mov_b32_e32 v52, v0
	v_mov_b32_e32 v53, v0
	v_mov_b32_e32 v54, v0
	v_mov_b32_e32 v55, v0
	v_mov_b32_e32 v56, v0
	v_mov_b32_e32 v57, v0
	v_mov_b32_e32 v58, v0
	v_mov_b32_e32 v59, v0
	v_mov_b32_e32 v60, v0
	v_mov_b32_e32 v61, v0
	v_mov_b32_e32 v62, v0
	v_mov_b32_e32 v63, v0
	v_mov_b32_e32 v64, v0
	v_mov_b32_e32 v65, v0
	v_mov_b32_e32 v66, v0
	v_mov_b32_e32 v67, v0
	v_mov_b32_e32 v68, v0
	v_mov_b32_e32 v69, v0
	v_mov_b32_e32 v70, v0
	v_mov_b32_e32 v71, v0
	v_mov_b32_e32 v72, v0
	v_mov_b32_e32 v73, v0
	v_mov_b32_e32 v74, v0
	v_mov_b32_e32 v75, v0
	v_mov_b32_e32 v76, v0
	v_mov_b32_e32 v77, v0
	v_mov_b32_e32 v78, v0
	v_mov_b32_e32 v79, v0
	v_mov_b32_e32 v84, v0
	v_mov_b32_e32 v85, v0
	v_mov_b32_e32 v86, v0
	v_mov_b32_e32 v87, v0
	v_mov_b32_e32 v92, v0
	v_mov_b32_e32 v93, v0
	v_mov_b32_e32 v94, v0
	v_mov_b32_e32 v95, v0
	v_mov_b32_e32 v100, v0
	v_mov_b32_e32 v101, v0
	v_mov_b32_e32 v102, v0
	v_mov_b32_e32 v103, v0
	v_mov_b32_e32 v108, v0
	v_mov_b32_e32 v109, v0
	v_mov_b32_e32 v110, v0
	v_mov_b32_e32 v111, v0
	v_mov_b32_e32 v80, v0
	v_mov_b32_e32 v81, v0
	v_mov_b32_e32 v82, v0
	v_mov_b32_e32 v83, v0
	v_mov_b32_e32 v88, v0
	v_mov_b32_e32 v89, v0
	v_mov_b32_e32 v90, v0
	v_mov_b32_e32 v91, v0
	v_mov_b32_e32 v96, v0
	v_mov_b32_e32 v97, v0
	v_mov_b32_e32 v98, v0
	v_mov_b32_e32 v99, v0
	v_mov_b32_e32 v104, v0
	v_mov_b32_e32 v105, v0
	v_mov_b32_e32 v106, v0
	v_mov_b32_e32 v107, v0
	v_mov_b32_e32 v112, v0
	v_mov_b32_e32 v113, v0
	v_mov_b32_e32 v114, v0
	v_mov_b32_e32 v115, v0
	v_mov_b32_e32 v116, v0
	v_mov_b32_e32 v117, v0
	v_mov_b32_e32 v118, v0
	v_mov_b32_e32 v119, v0
	v_mov_b32_e32 v120, v0
	v_mov_b32_e32 v121, v0
	v_mov_b32_e32 v122, v0
	v_mov_b32_e32 v123, v0
	v_mov_b32_e32 v124, v0
	v_mov_b32_e32 v125, v0
	v_mov_b32_e32 v126, v0
	v_mov_b32_e32 v127, v0
	v_add_u32_e32 v198, 0x10000, v242
	v_add_u32_e32 v199, 0x18000, v242
; #define PG8_STAGE(bufoff, gbase, voff) do { _Pragma("unroll") for (int _i = 0; _i < 2; ++_i) \
;         __builtin_amdgcn_global_load_lds((const unsigned*)((const char*)(gbase) + (voff)[_i]), (LAS unsigned*)(lds + (bufoff) + ldsw + _i * 8192), 16, 0, 0); } while (0)
; #define PG8_LDA(dst, b, h) do { _Pragma("unroll") for (int m = 0; m < 4; ++m) _Pragma("unroll") for (int k = 0; k < 2; ++k) dst[m][k] = *(const LAS bf16x8*)(lds + PG8_SA(b, h) + aoff + m * 2048 + k * 1024); } while (0)
; #define PG8_LDB(dst, b, h) do { _Pragma("unroll") for (int n = 0; n < 2; ++n) _Pragma("unroll") for (int k = 0; k < 2; ++k) dst[n][k] = *(const LAS bf16x8*)(lds + PG8_SB(b, h) + boff + n * 2048 + k * 1024); } while (0)
; #define PG8_MMA(ai, bj, At, Bt) do { __builtin_amdgcn_s_setprio(1); _Pragma("unroll") for (int m = 0; m < 4; ++m) _Pragma("unroll") for (int n = 0; n < 2; ++n) _Pragma("unroll") for (int k = 0; k < 2; ++k) \
;         acc[ai][bj][m][n] = __builtin_amdgcn_mfma_f32_16x16x32_bf16(Bt[n][k], At[m][k], acc[ai][bj][m][n], 0, 0, 0); __builtin_amdgcn_s_setprio(0); } while (0)
; #define PG8_WAIT_V(n) asm volatile("s_waitcnt vmcnt(" #n ")" ::: "memory")
; #define PG8_WAIT_L(n) asm volatile("s_waitcnt lgkmcnt(" #n ")" ::: "memory")
; #define PG8_BAR __builtin_amdgcn_s_barrier()
; #define PG8_SCHED __builtin_amdgcn_sched_barrier(0)
; template <class Epi, class Addr>
; __device__ __forceinline__ void gemm_phase(LAS unsigned char* lds, const Gemm g, const StaticOrder& S, const Addr& AD, const Epi& E) {
;     ...
;         for (int t = 0; t < nt; t += 2) {
;             const bool last = (t == nt - 2);
;             const char* a1 = cA + (size_t)(t + 1) * kstep;
;             const char* a2 = last ? nA : cA + (size_t)(t + 2) * kstep; const char* b2 = last ? nB : cB + (size_t)(t + 2) * kstep;
;             const char* a3 = a2 + kstep; const char* b3 = b2 + kstep;
;             PG8_LDB(B0, 0, 0); PG8_LDB(B1, 0, 1); PG8_SCHED; PG8_LDA(At, 0, 0); PG8_STAGE(PG8_SA(1, 1), a1 + hstepA, voffA);
;             PG8_WAIT_V(8); PG8_WAIT_L(0); PG8_BAR; PG8_MMA(0, 0, At, B0); PG8_MMA(0, 1, At, B1); PG8_BAR; PG8_SCHED;
;             PG8_LDA(At, 0, 1); PG8_STAGE(PG8_SB(0, 0), b2, voffB); PG8_STAGE(PG8_SB(0, 1), b2 + hstepB, voffB); PG8_STAGE(PG8_SA(0, 0), a2, voffA);
;             PG8_WAIT_V(8); PG8_WAIT_L(0); PG8_BAR; PG8_MMA(1, 0, At, B0); PG8_MMA(1, 1, At, B1); PG8_BAR; PG8_SCHED;
.LBB0_1332:
	s_add_i32 s81, s66, 2
	s_add_u32 s6, s8, 0x100
	s_addc_u32 s7, s9, 0
	s_add_i32 s24, 0, 0x10000
	s_cmp_eq_u32 s74, s66
	s_cselect_b32 s69, s63, s7
	s_cselect_b32 s68, s62, s6
	s_cselect_b32 s67, s65, s80
	s_cselect_b32 s66, s64, s79
	s_add_i32 s25, 0, 0x14000
	ds_read_b128 v[134:137], v198
	ds_read_b128 v[138:141], v198 offset:1024
	ds_read_b128 v[142:145], v198 offset:2048
	ds_read_b128 v[146:149], v198 offset:3072
	ds_read_b128 v[150:153], v198 offset:16384
	ds_read_b128 v[154:157], v198 offset:17408
	ds_read_b128 v[158:161], v198 offset:18432
	ds_read_b128 v[162:165], v198 offset:19456
	s_add_i32 m0, s17, 0xc000
	ds_read_b128 v[166:169], v243
	ds_read_b128 v[170:173], v243 offset:1024
	ds_read_b128 v[174:177], v243 offset:2048
	ds_read_b128 v[178:181], v243 offset:3072
	ds_read_b128 v[182:185], v243 offset:4096
	ds_read_b128 v[186:189], v243 offset:5120
	ds_read_b128 v[190:193], v243 offset:6144
	ds_read_b128 v[194:197], v243 offset:7168
	global_load_lds_dwordx4 v130, s[8:9]
	s_add_i32 m0, s17, 0xe000
	s_nop 0
	global_load_lds_dwordx4 v132, s[8:9]
	s_waitcnt vmcnt(8)
	s_waitcnt lgkmcnt(0)
	s_barrier
	s_setprio 1
	s_waitcnt lgkmcnt(0)
	v_mfma_f32_16x16x32_bf16 v[124:127], v[134:137], v[166:169], v[124:127]
	v_mfma_f32_16x16x32_bf16 v[120:123], v[142:145], v[166:169], v[120:123]
	v_mfma_f32_16x16x32_bf16 v[116:119], v[134:137], v[174:177], v[116:119]
	v_mfma_f32_16x16x32_bf16 v[112:115], v[142:145], v[174:177], v[112:115]
	v_mfma_f32_16x16x32_bf16 v[104:107], v[134:137], v[182:185], v[104:107]
	v_mfma_f32_16x16x32_bf16 v[96:99], v[142:145], v[182:185], v[96:99]
	v_mfma_f32_16x16x32_bf16 v[88:91], v[134:137], v[190:193], v[88:91]
	v_mfma_f32_16x16x32_bf16 v[80:83], v[142:145], v[190:193], v[80:83]
	v_mfma_f32_16x16x32_bf16 v[124:127], v[138:141], v[170:173], v[124:127]
	v_mfma_f32_16x16x32_bf16 v[120:123], v[146:149], v[170:173], v[120:123]
	v_mfma_f32_16x16x32_bf16 v[116:119], v[138:141], v[178:181], v[116:119]
	v_mfma_f32_16x16x32_bf16 v[112:115], v[146:149], v[178:181], v[112:115]
	v_mfma_f32_16x16x32_bf16 v[104:107], v[138:141], v[186:189], v[104:107]
	v_mfma_f32_16x16x32_bf16 v[96:99], v[146:149], v[186:189], v[96:99]
	v_mfma_f32_16x16x32_bf16 v[88:91], v[138:141], v[194:197], v[88:91]
	v_mfma_f32_16x16x32_bf16 v[80:83], v[146:149], v[194:197], v[80:83]
	s_setprio 0
	s_setprio 1
	v_mfma_f32_16x16x32_bf16 v[108:111], v[150:153], v[166:169], v[108:111]
	v_mfma_f32_16x16x32_bf16 v[100:103], v[158:161], v[166:169], v[100:103]
	v_mfma_f32_16x16x32_bf16 v[92:95], v[150:153], v[174:177], v[92:95]
	v_mfma_f32_16x16x32_bf16 v[84:87], v[158:161], v[174:177], v[84:87]
	v_mfma_f32_16x16x32_bf16 v[76:79], v[150:153], v[182:185], v[76:79]
	v_mfma_f32_16x16x32_bf16 v[72:75], v[158:161], v[182:185], v[72:75]
	v_mfma_f32_16x16x32_bf16 v[68:71], v[150:153], v[190:193], v[68:71]
	v_mfma_f32_16x16x32_bf16 v[64:67], v[158:161], v[190:193], v[64:67]
	v_mfma_f32_16x16x32_bf16 v[108:111], v[154:157], v[170:173], v[108:111]
	v_mfma_f32_16x16x32_bf16 v[100:103], v[162:165], v[170:173], v[100:103]
	v_mfma_f32_16x16x32_bf16 v[92:95], v[154:157], v[178:181], v[92:95]
	v_mfma_f32_16x16x32_bf16 v[84:87], v[162:165], v[178:181], v[84:87]
	v_mfma_f32_16x16x32_bf16 v[76:79], v[154:157], v[186:189], v[76:79]
	v_mfma_f32_16x16x32_bf16 v[72:75], v[162:165], v[186:189], v[72:75]
	v_mfma_f32_16x16x32_bf16 v[68:71], v[154:157], v[194:197], v[68:71]
	v_mfma_f32_16x16x32_bf16 v[64:67], v[162:165], v[194:197], v[64:67]
	s_setprio 0
	s_barrier
	s_add_i32 s8, s24, s2
	s_mov_b32 m0, s8
	ds_read_b128 v[166:169], v243 offset:16384
	ds_read_b128 v[170:173], v243 offset:17408
	ds_read_b128 v[174:177], v243 offset:18432
	ds_read_b128 v[178:181], v243 offset:19456
	ds_read_b128 v[182:185], v243 offset:20480
	ds_read_b128 v[186:189], v243 offset:21504
	ds_read_b128 v[190:193], v243 offset:22528
	ds_read_b128 v[194:197], v243 offset:23552
	global_load_lds_dwordx4 v200, s[66:67]
	s_add_i32 m0, s8, 0x2000
	s_add_u32 s8, s66, 0xb0000
	s_addc_u32 s9, s67, 0
	s_add_i32 s24, s25, s2
	global_load_lds_dwordx4 v128, s[66:67]
	s_mov_b32 m0, s24
	s_nop 0
	global_load_lds_dwordx4 v200, s[8:9]
	s_add_i32 m0, s24, 0x2000
	s_nop 0
	global_load_lds_dwordx4 v128, s[8:9]
	s_mov_b32 m0, s17
	s_nop 0
	global_load_lds_dwordx4 v200, s[68:69]
	s_mov_b32 m0, s18
	s_nop 0
	global_load_lds_dwordx4 v128, s[68:69]
	s_waitcnt vmcnt(8)
	s_waitcnt lgkmcnt(0)
	s_barrier
	s_setprio 1
	s_waitcnt lgkmcnt(0)
	v_mfma_f32_16x16x32_bf16 v[60:63], v[134:137], v[166:169], v[60:63]
	v_mfma_f32_16x16x32_bf16 v[56:59], v[142:145], v[166:169], v[56:59]
	v_mfma_f32_16x16x32_bf16 v[52:55], v[134:137], v[174:177], v[52:55]
	v_mfma_f32_16x16x32_bf16 v[48:51], v[142:145], v[174:177], v[48:51]
	v_mfma_f32_16x16x32_bf16 v[40:43], v[134:137], v[182:185], v[40:43]
	v_mfma_f32_16x16x32_bf16 v[32:35], v[142:145], v[182:185], v[32:35]
	v_mfma_f32_16x16x32_bf16 v[24:27], v[134:137], v[190:193], v[24:27]
	v_mfma_f32_16x16x32_bf16 v[16:19], v[142:145], v[190:193], v[16:19]
	v_mfma_f32_16x16x32_bf16 v[60:63], v[138:141], v[170:173], v[60:63]
	v_mfma_f32_16x16x32_bf16 v[56:59], v[146:149], v[170:173], v[56:59]
	v_mfma_f32_16x16x32_bf16 v[52:55], v[138:141], v[178:181], v[52:55]
	v_mfma_f32_16x16x32_bf16 v[48:51], v[146:149], v[178:181], v[48:51]
	v_mfma_f32_16x16x32_bf16 v[40:43], v[138:141], v[186:189], v[40:43]
	v_mfma_f32_16x16x32_bf16 v[32:35], v[146:149], v[186:189], v[32:35]
	v_mfma_f32_16x16x32_bf16 v[24:27], v[138:141], v[194:197], v[24:27]
	v_mfma_f32_16x16x32_bf16 v[16:19], v[146:149], v[194:197], v[16:19]
	s_setprio 0
	s_setprio 1
	v_mfma_f32_16x16x32_bf16 v[44:47], v[150:153], v[166:169], v[44:47]
	v_mfma_f32_16x16x32_bf16 v[36:39], v[158:161], v[166:169], v[36:39]
	v_mfma_f32_16x16x32_bf16 v[28:31], v[150:153], v[174:177], v[28:31]
	v_mfma_f32_16x16x32_bf16 v[20:23], v[158:161], v[174:177], v[20:23]
	v_mfma_f32_16x16x32_bf16 v[12:15], v[150:153], v[182:185], v[12:15]
	v_mfma_f32_16x16x32_bf16 v[8:11], v[158:161], v[182:185], v[8:11]
	v_mfma_f32_16x16x32_bf16 v[4:7], v[150:153], v[190:193], v[4:7]
	v_mfma_f32_16x16x32_bf16 v[0:3], v[158:161], v[190:193], v[0:3]
	v_mfma_f32_16x16x32_bf16 v[44:47], v[154:157], v[170:173], v[44:47]
	v_mfma_f32_16x16x32_bf16 v[36:39], v[162:165], v[170:173], v[36:39]
	v_mfma_f32_16x16x32_bf16 v[28:31], v[154:157], v[178:181], v[28:31]
	v_mfma_f32_16x16x32_bf16 v[20:23], v[162:165], v[178:181], v[20:23]
	v_mfma_f32_16x16x32_bf16 v[12:15], v[154:157], v[186:189], v[12:15]
	v_mfma_f32_16x16x32_bf16 v[8:11], v[162:165], v[186:189], v[8:11]
	v_mfma_f32_16x16x32_bf16 v[4:7], v[154:157], v[194:197], v[4:7]
	v_mfma_f32_16x16x32_bf16 v[0:3], v[162:165], v[194:197], v[0:3]
	s_setprio 0
	s_barrier
; #define PG8_STAGE(bufoff, gbase, voff) do { _Pragma("unroll") for (int _i = 0; _i < 2; ++_i) \
;         __builtin_amdgcn_global_load_lds((const unsigned*)((const char*)(gbase) + (voff)[_i]), (LAS unsigned*)(lds + (bufoff) + ldsw + _i * 8192), 16, 0, 0); } while (0)
; #define PG8_LDA(dst, b, h) do { _Pragma("unroll") for (int m = 0; m < 4; ++m) _Pragma("unroll") for (int k = 0; k < 2; ++k) dst[m][k] = *(const LAS bf16x8*)(lds + PG8_SA(b, h) + aoff + m * 2048 + k * 1024); } while (0)
; #define PG8_LDB(dst, b, h) do { _Pragma("unroll") for (int n = 0; n < 2; ++n) _Pragma("unroll") for (int k = 0; k < 2; ++k) dst[n][k] = *(const LAS bf16x8*)(lds + PG8_SB(b, h) + boff + n * 2048 + k * 1024); } while (0)
; #define PG8_MMA(ai, bj, At, Bt) do { __builtin_amdgcn_s_setprio(1); _Pragma("unroll") for (int m = 0; m < 4; ++m) _Pragma("unroll") for (int n = 0; n < 2; ++n) _Pragma("unroll") for (int k = 0; k < 2; ++k) \
;         acc[ai][bj][m][n] = __builtin_amdgcn_mfma_f32_16x16x32_bf16(Bt[n][k], At[m][k], acc[ai][bj][m][n], 0, 0, 0); __builtin_amdgcn_s_setprio(0); } while (0)
; #define PG8_WAIT_V(n) asm volatile("s_waitcnt vmcnt(" #n ")" ::: "memory")
; #define PG8_WAIT_L(n) asm volatile("s_waitcnt lgkmcnt(" #n ")" ::: "memory")
; #define PG8_BAR __builtin_amdgcn_s_barrier()
; #define PG8_SCHED __builtin_amdgcn_sched_barrier(0)
; template <class Epi, class Addr>
; __device__ __forceinline__ void gemm_phase(LAS unsigned char* lds, const Gemm g, const StaticOrder& S, const Addr& AD, const Epi& E) {
;     ...
;             PG8_LDB(B0, 1, 0); PG8_LDB(B1, 1, 1); PG8_SCHED; PG8_LDA(At, 1, 0); PG8_STAGE(PG8_SA(0, 1), a2 + hstepA, voffA);
;             PG8_WAIT_V(8); PG8_WAIT_L(0); PG8_BAR; PG8_MMA(0, 0, At, B0); PG8_MMA(0, 1, At, B1); PG8_BAR; PG8_SCHED;
;             PG8_LDA(At, 1, 1); PG8_STAGE(PG8_SB(1, 0), b3, voffB); PG8_STAGE(PG8_SB(1, 1), b3 + hstepB, voffB); PG8_STAGE(PG8_SA(1, 0), a3, voffA);
;             PG8_WAIT_V(8); PG8_WAIT_L(0); PG8_BAR; PG8_MMA(1, 0, At, B0); PG8_MMA(1, 1, At, B1); PG8_BAR; PG8_SCHED;
	s_add_i32 s24, 0, 0x18000
	s_add_i32 s25, 0, 0x1c000
	ds_read_b128 v[134:137], v199
	ds_read_b128 v[138:141], v199 offset:1024
	ds_read_b128 v[142:145], v199 offset:2048
	ds_read_b128 v[146:149], v199 offset:3072
	ds_read_b128 v[150:153], v199 offset:16384
	ds_read_b128 v[154:157], v199 offset:17408
	ds_read_b128 v[158:161], v199 offset:18432
	ds_read_b128 v[162:165], v199 offset:19456
	s_add_u32 s8, s68, 0xb0000
	s_addc_u32 s9, s69, 0
	s_mov_b32 m0, s19
	ds_read_b128 v[166:169], v243 offset:32768
	ds_read_b128 v[170:173], v243 offset:33792
	ds_read_b128 v[174:177], v243 offset:34816
	ds_read_b128 v[178:181], v243 offset:35840
	ds_read_b128 v[182:185], v243 offset:36864
	ds_read_b128 v[186:189], v243 offset:37888
	ds_read_b128 v[190:193], v243 offset:38912
	ds_read_b128 v[194:197], v243 offset:39936
	global_load_lds_dwordx4 v200, s[8:9]
	s_mov_b32 m0, s20
	s_nop 0
	global_load_lds_dwordx4 v128, s[8:9]
	s_waitcnt vmcnt(8)
	s_waitcnt lgkmcnt(0)
	s_barrier
	s_setprio 1
	s_waitcnt lgkmcnt(0)
	v_mfma_f32_16x16x32_bf16 v[124:127], v[134:137], v[166:169], v[124:127]
	v_mfma_f32_16x16x32_bf16 v[120:123], v[142:145], v[166:169], v[120:123]
	v_mfma_f32_16x16x32_bf16 v[116:119], v[134:137], v[174:177], v[116:119]
	v_mfma_f32_16x16x32_bf16 v[112:115], v[142:145], v[174:177], v[112:115]
	v_mfma_f32_16x16x32_bf16 v[104:107], v[134:137], v[182:185], v[104:107]
	v_mfma_f32_16x16x32_bf16 v[96:99], v[142:145], v[182:185], v[96:99]
	v_mfma_f32_16x16x32_bf16 v[88:91], v[134:137], v[190:193], v[88:91]
	v_mfma_f32_16x16x32_bf16 v[80:83], v[142:145], v[190:193], v[80:83]
	v_mfma_f32_16x16x32_bf16 v[124:127], v[138:141], v[170:173], v[124:127]
	v_mfma_f32_16x16x32_bf16 v[120:123], v[146:149], v[170:173], v[120:123]
	v_mfma_f32_16x16x32_bf16 v[116:119], v[138:141], v[178:181], v[116:119]
	v_mfma_f32_16x16x32_bf16 v[112:115], v[146:149], v[178:181], v[112:115]
	v_mfma_f32_16x16x32_bf16 v[104:107], v[138:141], v[186:189], v[104:107]
	v_mfma_f32_16x16x32_bf16 v[96:99], v[146:149], v[186:189], v[96:99]
	v_mfma_f32_16x16x32_bf16 v[88:91], v[138:141], v[194:197], v[88:91]
	v_mfma_f32_16x16x32_bf16 v[80:83], v[146:149], v[194:197], v[80:83]
	s_setprio 0
	s_setprio 1
	v_mfma_f32_16x16x32_bf16 v[108:111], v[150:153], v[166:169], v[108:111]
	v_mfma_f32_16x16x32_bf16 v[100:103], v[158:161], v[166:169], v[100:103]
	v_mfma_f32_16x16x32_bf16 v[92:95], v[150:153], v[174:177], v[92:95]
	v_mfma_f32_16x16x32_bf16 v[84:87], v[158:161], v[174:177], v[84:87]
	v_mfma_f32_16x16x32_bf16 v[76:79], v[150:153], v[182:185], v[76:79]
	v_mfma_f32_16x16x32_bf16 v[72:75], v[158:161], v[182:185], v[72:75]
	v_mfma_f32_16x16x32_bf16 v[68:71], v[150:153], v[190:193], v[68:71]
	v_mfma_f32_16x16x32_bf16 v[64:67], v[158:161], v[190:193], v[64:67]
	v_mfma_f32_16x16x32_bf16 v[108:111], v[154:157], v[170:173], v[108:111]
	v_mfma_f32_16x16x32_bf16 v[100:103], v[162:165], v[170:173], v[100:103]
	v_mfma_f32_16x16x32_bf16 v[92:95], v[154:157], v[178:181], v[92:95]
	v_mfma_f32_16x16x32_bf16 v[84:87], v[162:165], v[178:181], v[84:87]
	v_mfma_f32_16x16x32_bf16 v[76:79], v[154:157], v[186:189], v[76:79]
	v_mfma_f32_16x16x32_bf16 v[72:75], v[162:165], v[186:189], v[72:75]
	v_mfma_f32_16x16x32_bf16 v[68:71], v[154:157], v[194:197], v[68:71]
	v_mfma_f32_16x16x32_bf16 v[64:67], v[162:165], v[194:197], v[64:67]
	s_setprio 0
	s_barrier
	s_add_i32 s8, s24, s2
	s_mov_b32 m0, s8
	s_add_u32 s8, s66, 0x80
	s_addc_u32 s9, s67, 0
	ds_read_b128 v[166:169], v243 offset:49152
	ds_read_b128 v[170:173], v243 offset:50176
	ds_read_b128 v[174:177], v243 offset:51200
	ds_read_b128 v[178:181], v243 offset:52224
	ds_read_b128 v[182:185], v243 offset:53248
	ds_read_b128 v[186:189], v243 offset:54272
	ds_read_b128 v[190:193], v243 offset:55296
	ds_read_b128 v[194:197], v243 offset:56320
	global_load_lds_dwordx4 v200, s[8:9]
	s_add_i32 m0, m0, 0x2000
	s_add_i32 s24, s25, s2
	s_nop 0
	global_load_lds_dwordx4 v128, s[8:9]
	s_add_u32 s8, s66, 0xb0080
	s_addc_u32 s9, s67, 0
	s_mov_b32 m0, s24
	s_nop 0
	global_load_lds_dwordx4 v200, s[8:9]
	s_add_i32 m0, s24, 0x2000
	s_nop 0
	global_load_lds_dwordx4 v128, s[8:9]
	s_add_u32 s8, s68, 0x80
	s_addc_u32 s9, s69, 0
	s_mov_b32 m0, s72
	s_nop 0
	global_load_lds_dwordx4 v200, s[8:9]
	s_mov_b32 m0, s73
	s_nop 0
	global_load_lds_dwordx4 v128, s[8:9]
	s_waitcnt vmcnt(8)
	s_waitcnt lgkmcnt(0)
	s_barrier
; #define PG8_MMA(ai, bj, At, Bt) do { __builtin_amdgcn_s_setprio(1); _Pragma("unroll") for (int m = 0; m < 4; ++m) _Pragma("unroll") for (int n = 0; n < 2; ++n) _Pragma("unroll") for (int k = 0; k < 2; ++k) \
;         acc[ai][bj][m][n] = __builtin_amdgcn_mfma_f32_16x16x32_bf16(Bt[n][k], At[m][k], acc[ai][bj][m][n], 0, 0, 0); __builtin_amdgcn_s_setprio(0); } while (0)
; #define PG8_WAIT_V(n) asm volatile("s_waitcnt vmcnt(" #n ")" ::: "memory")
; #define PG8_WAIT_L(n) asm volatile("s_waitcnt lgkmcnt(" #n ")" ::: "memory")
; #define PG8_BAR __builtin_amdgcn_s_barrier()
; #define PG8_SCHED __builtin_amdgcn_sched_barrier(0)
;     __device__ __forceinline__ void operator()(Acc& acc, const Unit& u, int wr, int wc, int fr, int fq, LAS unsigned char* xch) const {
;     ...
;             for (int q = 0; q < 4; ++q) v[q] = pre[g % PD][q] + acc[ai][q >> 1][m][q & 1] * alpha;
; template <class Epi, class Addr>
; __device__ __forceinline__ void gemm_phase(LAS unsigned char* lds, const Gemm g, const StaticOrder& S, const Addr& AD, const Epi& E) {
;     ...
;             PG8_WAIT_V(8); PG8_WAIT_L(0); PG8_BAR; PG8_MMA(1, 0, At, B0); PG8_MMA(1, 1, At, B1); PG8_BAR; PG8_SCHED;
;         }
	s_setprio 1
	s_waitcnt lgkmcnt(0)
	v_mfma_f32_16x16x32_bf16 v[60:63], v[134:137], v[166:169], v[60:63]
	v_mfma_f32_16x16x32_bf16 v[56:59], v[142:145], v[166:169], v[56:59]
	v_mfma_f32_16x16x32_bf16 v[52:55], v[134:137], v[174:177], v[52:55]
	v_mfma_f32_16x16x32_bf16 v[48:51], v[142:145], v[174:177], v[48:51]
	v_mfma_f32_16x16x32_bf16 v[40:43], v[134:137], v[182:185], v[40:43]
	v_mfma_f32_16x16x32_bf16 v[32:35], v[142:145], v[182:185], v[32:35]
	v_mfma_f32_16x16x32_bf16 v[24:27], v[134:137], v[190:193], v[24:27]
	v_mfma_f32_16x16x32_bf16 v[16:19], v[142:145], v[190:193], v[16:19]
	v_mfma_f32_16x16x32_bf16 v[60:63], v[138:141], v[170:173], v[60:63]
	v_mfma_f32_16x16x32_bf16 v[56:59], v[146:149], v[170:173], v[56:59]
	v_mfma_f32_16x16x32_bf16 v[52:55], v[138:141], v[178:181], v[52:55]
	v_mfma_f32_16x16x32_bf16 v[48:51], v[146:149], v[178:181], v[48:51]
	v_mfma_f32_16x16x32_bf16 v[40:43], v[138:141], v[186:189], v[40:43]
	v_mfma_f32_16x16x32_bf16 v[32:35], v[146:149], v[186:189], v[32:35]
	v_mfma_f32_16x16x32_bf16 v[24:27], v[138:141], v[194:197], v[24:27]
	v_mfma_f32_16x16x32_bf16 v[16:19], v[146:149], v[194:197], v[16:19]
	s_setprio 0
	s_setprio 1
	v_mfma_f32_16x16x32_bf16 v[44:47], v[150:153], v[166:169], v[44:47]
	v_mfma_f32_16x16x32_bf16 v[36:39], v[158:161], v[166:169], v[36:39]
	v_mfma_f32_16x16x32_bf16 v[28:31], v[150:153], v[174:177], v[28:31]
	v_mfma_f32_16x16x32_bf16 v[20:23], v[158:161], v[174:177], v[20:23]
	v_mfma_f32_16x16x32_bf16 v[12:15], v[150:153], v[182:185], v[12:15]
	v_mfma_f32_16x16x32_bf16 v[8:11], v[158:161], v[182:185], v[8:11]
	v_mfma_f32_16x16x32_bf16 v[4:7], v[150:153], v[190:193], v[4:7]
	v_mfma_f32_16x16x32_bf16 v[0:3], v[158:161], v[190:193], v[0:3]
	v_mfma_f32_16x16x32_bf16 v[44:47], v[154:157], v[170:173], v[44:47]
	v_mfma_f32_16x16x32_bf16 v[36:39], v[162:165], v[170:173], v[36:39]
	v_mfma_f32_16x16x32_bf16 v[28:31], v[154:157], v[178:181], v[28:31]
	v_mfma_f32_16x16x32_bf16 v[20:23], v[162:165], v[178:181], v[20:23]
	v_mfma_f32_16x16x32_bf16 v[12:15], v[154:157], v[186:189], v[12:15]
	v_mfma_f32_16x16x32_bf16 v[8:11], v[162:165], v[186:189], v[8:11]
	v_mfma_f32_16x16x32_bf16 v[4:7], v[154:157], v[194:197], v[4:7]
	v_mfma_f32_16x16x32_bf16 v[0:3], v[162:165], v[194:197], v[0:3]
	s_setprio 0
	s_barrier
	s_add_u32 s79, s79, 0x100
	s_addc_u32 s80, s80, 0
	s_cmp_ge_i32 s81, s23
	s_mov_b64 s[8:9], s[6:7]
	s_mov_b32 s66, s81
	s_cbranch_scc0 .LBB0_1332
	v_pk_mul_f32 v[188:189], v[126:127], 0.5 op_sel_hi:[1,0]
	v_pk_mul_f32 v[226:227], v[124:125], 0.5 op_sel_hi:[1,0]
	v_pk_mul_f32 v[196:197], v[122:123], 0.5 op_sel_hi:[1,0]
	v_pk_mul_f32 v[194:195], v[120:121], 0.5 op_sel_hi:[1,0]
	v_pk_mul_f32 v[222:223], v[110:111], 0.5 op_sel_hi:[1,0]
	v_pk_mul_f32 v[198:199], v[108:109], 0.5 op_sel_hi:[1,0]
	v_pk_mul_f32 v[192:193], v[102:103], 0.5 op_sel_hi:[1,0]
	v_pk_mul_f32 v[190:191], v[100:101], 0.5 op_sel_hi:[1,0]
	v_pk_mul_f32 v[184:185], v[118:119], 0.5 op_sel_hi:[1,0]
	v_pk_mul_f32 v[186:187], v[116:117], 0.5 op_sel_hi:[1,0]
	v_pk_mul_f32 v[178:179], v[114:115], 0.5 op_sel_hi:[1,0]
	v_pk_mul_f32 v[176:177], v[112:113], 0.5 op_sel_hi:[1,0]
	v_pk_mul_f32 v[182:183], v[94:95], 0.5 op_sel_hi:[1,0]
	v_pk_mul_f32 v[180:181], v[92:93], 0.5 op_sel_hi:[1,0]
	v_pk_mul_f32 v[170:171], v[86:87], 0.5 op_sel_hi:[1,0]
	v_pk_mul_f32 v[168:169], v[84:85], 0.5 op_sel_hi:[1,0]
	v_pk_mul_f32 v[164:165], v[106:107], 0.5 op_sel_hi:[1,0]
	v_pk_mul_f32 v[166:167], v[104:105], 0.5 op_sel_hi:[1,0]
	v_pk_mul_f32 v[158:159], v[98:99], 0.5 op_sel_hi:[1,0]
	v_pk_mul_f32 v[156:157], v[96:97], 0.5 op_sel_hi:[1,0]
	v_pk_mul_f32 v[162:163], v[78:79], 0.5 op_sel_hi:[1,0]
	v_pk_mul_f32 v[160:161], v[76:77], 0.5 op_sel_hi:[1,0]
	v_pk_mul_f32 v[154:155], v[74:75], 0.5 op_sel_hi:[1,0]
	v_pk_mul_f32 v[152:153], v[72:73], 0.5 op_sel_hi:[1,0]
	v_pk_mul_f32 v[148:149], v[90:91], 0.5 op_sel_hi:[1,0]
	v_pk_mul_f32 v[150:151], v[88:89], 0.5 op_sel_hi:[1,0]
	v_pk_mul_f32 v[142:143], v[82:83], 0.5 op_sel_hi:[1,0]
	v_pk_mul_f32 v[140:141], v[80:81], 0.5 op_sel_hi:[1,0]
	v_pk_mul_f32 v[146:147], v[70:71], 0.5 op_sel_hi:[1,0]
	v_pk_mul_f32 v[144:145], v[68:69], 0.5 op_sel_hi:[1,0]
	v_pk_mul_f32 v[138:139], v[66:67], 0.5 op_sel_hi:[1,0]
	v_pk_mul_f32 v[136:137], v[64:65], 0.5 op_sel_hi:[1,0]
	v_pk_mul_f32 v[126:127], v[62:63], 0.5 op_sel_hi:[1,0]
	v_pk_mul_f32 v[134:135], v[60:61], 0.5 op_sel_hi:[1,0]
	v_pk_mul_f32 v[118:119], v[58:59], 0.5 op_sel_hi:[1,0]
	v_pk_mul_f32 v[116:117], v[56:57], 0.5 op_sel_hi:[1,0]
	v_pk_mul_f32 v[122:123], v[46:47], 0.5 op_sel_hi:[1,0]
	v_pk_mul_f32 v[120:121], v[44:45], 0.5 op_sel_hi:[1,0]
	v_pk_mul_f32 v[114:115], v[38:39], 0.5 op_sel_hi:[1,0]
	v_pk_mul_f32 v[112:113], v[36:37], 0.5 op_sel_hi:[1,0]
	v_pk_mul_f32 v[110:111], v[54:55], 0.5 op_sel_hi:[1,0]
	v_pk_mul_f32 v[108:109], v[52:53], 0.5 op_sel_hi:[1,0]
	v_pk_mul_f32 v[102:103], v[50:51], 0.5 op_sel_hi:[1,0]
	v_pk_mul_f32 v[100:101], v[48:49], 0.5 op_sel_hi:[1,0]
	v_pk_mul_f32 v[106:107], v[30:31], 0.5 op_sel_hi:[1,0]
	v_pk_mul_f32 v[104:105], v[28:29], 0.5 op_sel_hi:[1,0]
	v_pk_mul_f32 v[98:99], v[22:23], 0.5 op_sel_hi:[1,0]
	v_pk_mul_f32 v[96:97], v[20:21], 0.5 op_sel_hi:[1,0]
	v_pk_mul_f32 v[94:95], v[42:43], 0.5 op_sel_hi:[1,0]
	v_pk_mul_f32 v[92:93], v[40:41], 0.5 op_sel_hi:[1,0]
	v_pk_mul_f32 v[86:87], v[34:35], 0.5 op_sel_hi:[1,0]
	v_pk_mul_f32 v[84:85], v[32:33], 0.5 op_sel_hi:[1,0]
	v_pk_mul_f32 v[90:91], v[14:15], 0.5 op_sel_hi:[1,0]
	v_pk_mul_f32 v[88:89], v[12:13], 0.5 op_sel_hi:[1,0]
	v_pk_mul_f32 v[82:83], v[10:11], 0.5 op_sel_hi:[1,0]
	v_pk_mul_f32 v[80:81], v[8:9], 0.5 op_sel_hi:[1,0]
	v_pk_mul_f32 v[78:79], v[26:27], 0.5 op_sel_hi:[1,0]
	v_pk_mul_f32 v[76:77], v[24:25], 0.5 op_sel_hi:[1,0]
	v_pk_mul_f32 v[70:71], v[18:19], 0.5 op_sel_hi:[1,0]
	v_pk_mul_f32 v[68:69], v[16:17], 0.5 op_sel_hi:[1,0]
	v_pk_mul_f32 v[74:75], v[6:7], 0.5 op_sel_hi:[1,0]
	v_pk_mul_f32 v[72:73], v[4:5], 0.5 op_sel_hi:[1,0]
	v_pk_mul_f32 v[66:67], v[2:3], 0.5 op_sel_hi:[1,0]
	v_pk_mul_f32 v[64:65], v[0:1], 0.5 op_sel_hi:[1,0]
